# up_proj epilogue: neighbour-row LDS reads of the first column pass issued before the wait for the tap weights (waits to first consumer)
# baseline (speedup 1.0000x reference)
.LBB0_1339:
	v_and_b32_e32 v56, 15, v0
	v_bfe_u32 v57, v0, 4, 2
	s_lshl_b32 s8, s12, 8
	s_add_i32 s8, s8, s63
	s_lshl_b32 s9, s13, 9
	s_lshl_b32 s22, s64, 2
	s_add_i32 s9, s9, s22
	v_lshl_add_u32 v235, v57, 5, s9
	global_load_dwordx4 v[100:103], v235, s[0:1]
	global_load_dwordx4 v[104:107], v235, s[30:31]
	global_load_dwordx4 v[112:115], v235, s[34:35]
	global_load_dwordx4 v[120:123], v235, s[2:3]
	global_load_dwordx4 v[92:95], v235, s[36:37]
	global_load_dwordx4 v[96:99], v235, s[48:49]
	global_load_dwordx4 v[108:111], v235, s[46:47]
	global_load_dwordx4 v[116:119], v235, s[44:45]
	v_cmp_lt_u32_e64 s[10:11], 13, v56
	v_cmp_gt_u32_e64 s[14:15], 2, v56
	v_cmp_eq_u32_e64 s[22:23], 0, v56
	v_lshlrev_b32_e32 v217, 8, v56
	v_lshl_add_u32 v217, v57, 5, v217
	v_add_u32_e32 v217, 0xfffff200, v217
	v_cndmask_b32_e64 v250, 0, 1.0, s[22:23]
	v_cndmask_b32_e64 v251, 0, 1.0, s[14:15]
	v_mul_u32_u24_e32 v234, 0x2c00, v56
	v_lshl_add_u32 v234, v57, 4, v234
	s_mov_b32 s41, 0xbfb8aa3b
	v_mov_b32_e32 v240, 0xbfb8aa3b
	v_mov_b32_e32 v241, 1.0
	s_lshl_b32 s39, s12, 8
	s_add_i32 s39, s39, s63
	s_mul_i32 s39, s39, 0x2c00
	s_lshl_b32 s40, s13, 8
	s_add_i32 s39, s39, s40
	s_lshl_b32 s40, s64, 1
	s_add_i32 s39, s39, s40
	s_add_u32 s16, s70, s39
	s_addc_u32 s17, s71, 0
	s_add_u32 s18, s16, 0x160000
	s_addc_u32 s19, s17, 0
	v_pk_mul_f32 v[192:193], v[192:193], v[242:243] op_sel_hi:[1,0]
	v_pk_mul_f32 v[194:195], v[194:195], v[242:243] op_sel_hi:[1,0]
	v_pk_mul_f32 v[160:161], v[160:161], v[242:243] op_sel_hi:[1,0]
	v_pk_mul_f32 v[162:163], v[162:163], v[242:243] op_sel_hi:[1,0]
	v_pk_mul_f32 v[180:181], v[180:181], v[242:243] op_sel_hi:[1,0]
	v_pk_mul_f32 v[182:183], v[182:183], v[242:243] op_sel_hi:[1,0]
	v_pk_mul_f32 v[156:157], v[156:157], v[242:243] op_sel_hi:[1,0]
	v_pk_mul_f32 v[158:159], v[158:159], v[242:243] op_sel_hi:[1,0]
	v_pk_mul_f32 v[188:189], v[188:189], v[242:243] op_sel:[0,1] op_sel_hi:[1,1]
	v_pk_mul_f32 v[190:191], v[190:191], v[242:243] op_sel:[0,1] op_sel_hi:[1,1]
	v_pk_mul_f32 v[152:153], v[152:153], v[242:243] op_sel:[0,1] op_sel_hi:[1,1]
	v_pk_mul_f32 v[154:155], v[154:155], v[242:243] op_sel:[0,1] op_sel_hi:[1,1]
	v_pk_mul_f32 v[184:185], v[184:185], v[242:243] op_sel:[0,1] op_sel_hi:[1,1]
	v_pk_mul_f32 v[186:187], v[186:187], v[242:243] op_sel:[0,1] op_sel_hi:[1,1]
	v_pk_mul_f32 v[148:149], v[148:149], v[242:243] op_sel:[0,1] op_sel_hi:[1,1]
	v_pk_mul_f32 v[150:151], v[150:151], v[242:243] op_sel:[0,1] op_sel_hi:[1,1]
	v_pk_mul_f32 v[176:177], v[176:177], v[244:245] op_sel_hi:[1,0]
	v_pk_mul_f32 v[178:179], v[178:179], v[244:245] op_sel_hi:[1,0]
	v_pk_mul_f32 v[144:145], v[144:145], v[244:245] op_sel_hi:[1,0]
	v_pk_mul_f32 v[146:147], v[146:147], v[244:245] op_sel_hi:[1,0]
	v_pk_mul_f32 v[172:173], v[172:173], v[244:245] op_sel_hi:[1,0]
	v_pk_mul_f32 v[174:175], v[174:175], v[244:245] op_sel_hi:[1,0]
	v_pk_mul_f32 v[140:141], v[140:141], v[244:245] op_sel_hi:[1,0]
	v_pk_mul_f32 v[142:143], v[142:143], v[244:245] op_sel_hi:[1,0]
	v_pk_mul_f32 v[168:169], v[168:169], v[244:245] op_sel:[0,1] op_sel_hi:[1,1]
	v_pk_mul_f32 v[170:171], v[170:171], v[244:245] op_sel:[0,1] op_sel_hi:[1,1]
	v_pk_mul_f32 v[136:137], v[136:137], v[244:245] op_sel:[0,1] op_sel_hi:[1,1]
	v_pk_mul_f32 v[138:139], v[138:139], v[244:245] op_sel:[0,1] op_sel_hi:[1,1]
	v_pk_mul_f32 v[164:165], v[164:165], v[244:245] op_sel:[0,1] op_sel_hi:[1,1]
	v_pk_mul_f32 v[166:167], v[166:167], v[244:245] op_sel:[0,1] op_sel_hi:[1,1]
	v_pk_mul_f32 v[132:133], v[132:133], v[244:245] op_sel:[0,1] op_sel_hi:[1,1]
	v_pk_mul_f32 v[134:135], v[134:135], v[244:245] op_sel:[0,1] op_sel_hi:[1,1]
	v_pk_mul_f32 v[128:129], v[128:129], v[246:247] op_sel_hi:[1,0]
	v_pk_mul_f32 v[130:131], v[130:131], v[246:247] op_sel_hi:[1,0]
	v_pk_mul_f32 v[64:65], v[64:65], v[246:247] op_sel_hi:[1,0]
	v_pk_mul_f32 v[66:67], v[66:67], v[246:247] op_sel_hi:[1,0]
	v_pk_mul_f32 v[124:125], v[124:125], v[246:247] op_sel_hi:[1,0]
	v_pk_mul_f32 v[126:127], v[126:127], v[246:247] op_sel_hi:[1,0]
	v_pk_mul_f32 v[60:61], v[60:61], v[246:247] op_sel_hi:[1,0]
	v_pk_mul_f32 v[62:63], v[62:63], v[246:247] op_sel_hi:[1,0]
	v_pk_mul_f32 v[88:89], v[88:89], v[246:247] op_sel:[0,1] op_sel_hi:[1,1]
	v_pk_mul_f32 v[90:91], v[90:91], v[246:247] op_sel:[0,1] op_sel_hi:[1,1]
	v_pk_mul_f32 v[24:25], v[24:25], v[246:247] op_sel:[0,1] op_sel_hi:[1,1]
	v_pk_mul_f32 v[26:27], v[26:27], v[246:247] op_sel:[0,1] op_sel_hi:[1,1]
	v_pk_mul_f32 v[84:85], v[84:85], v[246:247] op_sel:[0,1] op_sel_hi:[1,1]
	v_pk_mul_f32 v[86:87], v[86:87], v[246:247] op_sel:[0,1] op_sel_hi:[1,1]
	v_pk_mul_f32 v[20:21], v[20:21], v[246:247] op_sel:[0,1] op_sel_hi:[1,1]
	v_pk_mul_f32 v[22:23], v[22:23], v[246:247] op_sel:[0,1] op_sel_hi:[1,1]
	v_pk_mul_f32 v[80:81], v[80:81], v[248:249] op_sel_hi:[1,0]
	v_pk_mul_f32 v[82:83], v[82:83], v[248:249] op_sel_hi:[1,0]
	v_pk_mul_f32 v[16:17], v[16:17], v[248:249] op_sel_hi:[1,0]
	v_pk_mul_f32 v[18:19], v[18:19], v[248:249] op_sel_hi:[1,0]
	v_pk_mul_f32 v[76:77], v[76:77], v[248:249] op_sel_hi:[1,0]
	v_pk_mul_f32 v[78:79], v[78:79], v[248:249] op_sel_hi:[1,0]
	v_pk_mul_f32 v[12:13], v[12:13], v[248:249] op_sel_hi:[1,0]
	v_pk_mul_f32 v[14:15], v[14:15], v[248:249] op_sel_hi:[1,0]
	v_pk_mul_f32 v[72:73], v[72:73], v[248:249] op_sel:[0,1] op_sel_hi:[1,1]
	v_pk_mul_f32 v[74:75], v[74:75], v[248:249] op_sel:[0,1] op_sel_hi:[1,1]
	v_pk_mul_f32 v[8:9], v[8:9], v[248:249] op_sel:[0,1] op_sel_hi:[1,1]
	v_pk_mul_f32 v[10:11], v[10:11], v[248:249] op_sel:[0,1] op_sel_hi:[1,1]
	v_pk_mul_f32 v[68:69], v[68:69], v[248:249] op_sel:[0,1] op_sel_hi:[1,1]
	v_pk_mul_f32 v[70:71], v[70:71], v[248:249] op_sel:[0,1] op_sel_hi:[1,1]
	v_pk_mul_f32 v[4:5], v[4:5], v[248:249] op_sel:[0,1] op_sel_hi:[1,1]
	v_pk_mul_f32 v[6:7], v[6:7], v[248:249] op_sel:[0,1] op_sel_hi:[1,1]
	v_add_u32_e32 v58, s78, v217
	s_and_saveexec_b64 s[8:9], s[10:11]
	ds_write_b128 v58, v[168:171]
	ds_write_b128 v58, v[136:139] offset:16
	ds_write_b128 v58, v[164:167] offset:128
	ds_write_b128 v58, v[132:135] offset:144
	ds_write_b128 v58, v[72:75] offset:4096
	ds_write_b128 v58, v[8:11] offset:4112
	ds_write_b128 v58, v[68:71] offset:4224
	ds_write_b128 v58, v[4:7] offset:4240
	s_mov_b64 exec, s[8:9]
	s_waitcnt lgkmcnt(0)
	s_barrier
	v_mov_b32_e32 v196, 0
	v_mov_b32_e32 v197, 0
	v_mov_b32_e32 v198, 0
	v_mov_b32_e32 v199, 0
	v_mov_b32_e32 v200, 0
	v_mov_b32_e32 v201, 0
	v_mov_b32_e32 v202, 0
	v_mov_b32_e32 v203, 0
	v_mov_b32_e32 v204, 0
	v_mov_b32_e32 v205, 0
	v_mov_b32_e32 v206, 0
	v_mov_b32_e32 v207, 0
	v_mov_b32_e32 v208, 0
	v_mov_b32_e32 v209, 0
	v_mov_b32_e32 v210, 0
	v_mov_b32_e32 v211, 0
	s_cmp_eq_u32 s63, 0
	s_cbranch_scc1 .Leu_pv0_skip_n0
	v_add_u32_e32 v58, s67, v217
	s_and_saveexec_b64 s[8:9], s[10:11]
	ds_read_b128 v[196:199], v58 offset:0
	ds_read_b128 v[200:203], v58 offset:128
	s_mov_b64 exec, s[8:9]
.Leu_pv0_skip_n0:
	s_cmp_eq_u32 s63, 0
	s_movk_i32 s40, 0x1000
	s_cselect_b32 s39, 0x800, s40
	s_add_i32 s39, s39, s67
	v_add_u32_e32 v59, s39, v217
	s_and_saveexec_b64 s[8:9], s[10:11]
	ds_read_b128 v[204:207], v59 offset:0
	ds_read_b128 v[208:211], v59 offset:128
	s_mov_b64 exec, s[8:9]
	s_waitcnt vmcnt(0)
	v_mul_f32_e32 v28, v104, v250
	v_mul_f32_e32 v29, v105, v250
	v_mul_f32_e32 v30, v106, v250
	v_mul_f32_e32 v31, v107, v250
	v_mul_f32_e32 v32, v100, v251
	v_mul_f32_e32 v33, v101, v251
	v_mul_f32_e32 v34, v102, v251
	v_mul_f32_e32 v35, v103, v251
	v_mul_f32_e32 v36, v96, v250
	v_mul_f32_e32 v37, v97, v250
	v_mul_f32_e32 v38, v98, v250
	v_mul_f32_e32 v39, v99, v250
	v_mul_f32_e32 v40, v92, v251
	v_mul_f32_e32 v41, v93, v251
	v_mul_f32_e32 v42, v94, v251
	v_mul_f32_e32 v43, v95, v251
	s_waitcnt lgkmcnt(0)
	v_pk_fma_f32 v[44:45], v[112:113], v[192:193], v[120:121]
	v_pk_fma_f32 v[46:47], v[114:115], v[194:195], v[122:123]
	v_pk_fma_f32 v[48:49], v[108:109], v[180:181], v[116:117]
	v_pk_fma_f32 v[50:51], v[110:111], v[182:183], v[118:119]
	v_fmac_f32_dpp v44, v192, v104 row_shr:1 row_mask:0xf bank_mask:0xf
	v_fmac_f32_dpp v45, v193, v105 row_shr:1 row_mask:0xf bank_mask:0xf
	v_fmac_f32_dpp v46, v194, v106 row_shr:1 row_mask:0xf bank_mask:0xf
	v_fmac_f32_dpp v47, v195, v107 row_shr:1 row_mask:0xf bank_mask:0xf
	v_fmac_f32_dpp v48, v180, v96 row_shr:1 row_mask:0xf bank_mask:0xf
	v_fmac_f32_dpp v49, v181, v97 row_shr:1 row_mask:0xf bank_mask:0xf
	v_fmac_f32_dpp v50, v182, v98 row_shr:1 row_mask:0xf bank_mask:0xf
	v_fmac_f32_dpp v51, v183, v99 row_shr:1 row_mask:0xf bank_mask:0xf
	v_fmac_f32_dpp v44, v192, v100 row_shr:2 row_mask:0xf bank_mask:0xf
	v_fmac_f32_dpp v45, v193, v101 row_shr:2 row_mask:0xf bank_mask:0xf
	v_fmac_f32_dpp v46, v194, v102 row_shr:2 row_mask:0xf bank_mask:0xf
	v_fmac_f32_dpp v47, v195, v103 row_shr:2 row_mask:0xf bank_mask:0xf
	v_fmac_f32_dpp v48, v180, v92 row_shr:2 row_mask:0xf bank_mask:0xf
	v_fmac_f32_dpp v49, v181, v93 row_shr:2 row_mask:0xf bank_mask:0xf
	v_fmac_f32_dpp v50, v182, v94 row_shr:2 row_mask:0xf bank_mask:0xf
	v_fmac_f32_dpp v51, v183, v95 row_shr:2 row_mask:0xf bank_mask:0xf
	v_fmac_f32_dpp v44, v196, v28 row_ror:1 row_mask:0xf bank_mask:0xf
	v_fmac_f32_dpp v45, v197, v29 row_ror:1 row_mask:0xf bank_mask:0xf
	v_fmac_f32_dpp v46, v198, v30 row_ror:1 row_mask:0xf bank_mask:0xf
	v_fmac_f32_dpp v47, v199, v31 row_ror:1 row_mask:0xf bank_mask:0xf
	v_fmac_f32_dpp v48, v200, v36 row_ror:1 row_mask:0xf bank_mask:0xf
	v_fmac_f32_dpp v49, v201, v37 row_ror:1 row_mask:0xf bank_mask:0xf
	v_fmac_f32_dpp v50, v202, v38 row_ror:1 row_mask:0xf bank_mask:0xf
	v_fmac_f32_dpp v51, v203, v39 row_ror:1 row_mask:0xf bank_mask:0xf
	v_fmac_f32_dpp v44, v196, v32 row_ror:2 row_mask:0xf bank_mask:0xf
	v_fmac_f32_dpp v45, v197, v33 row_ror:2 row_mask:0xf bank_mask:0xf
	v_fmac_f32_dpp v46, v198, v34 row_ror:2 row_mask:0xf bank_mask:0xf
	v_fmac_f32_dpp v47, v199, v35 row_ror:2 row_mask:0xf bank_mask:0xf
	v_fmac_f32_dpp v48, v200, v40 row_ror:2 row_mask:0xf bank_mask:0xf
	v_fmac_f32_dpp v49, v201, v41 row_ror:2 row_mask:0xf bank_mask:0xf
	v_fmac_f32_dpp v50, v202, v42 row_ror:2 row_mask:0xf bank_mask:0xf
	v_fmac_f32_dpp v51, v203, v43 row_ror:2 row_mask:0xf bank_mask:0xf
	v_pk_mul_f32 v[52:53], v[44:45], v[240:241] op_sel_hi:[1,0]
	v_pk_mul_f32 v[54:55], v[46:47], v[240:241] op_sel_hi:[1,0]
	v_exp_f32_e32 v52, v52
	v_exp_f32_e32 v53, v53
	v_exp_f32_e32 v54, v54
	v_exp_f32_e32 v55, v55
	v_pk_add_f32 v[52:53], v[52:53], v[240:241] op_sel:[0,1] op_sel_hi:[1,1]
	v_pk_add_f32 v[54:55], v[54:55], v[240:241] op_sel:[0,1] op_sel_hi:[1,1]
	v_rcp_f32_e32 v52, v52
	v_rcp_f32_e32 v53, v53
	v_rcp_f32_e32 v54, v54
	v_rcp_f32_e32 v55, v55
	v_pk_mul_f32 v[44:45], v[44:45], v[52:53]
	v_pk_mul_f32 v[46:47], v[46:47], v[54:55]
	v_pk_mul_f32 v[44:45], v[48:49], v[44:45]
	v_pk_mul_f32 v[46:47], v[50:51], v[46:47]
	v_cvt_pk_bf16_f32 v242, v44, v45
	v_cvt_pk_bf16_f32 v243, v46, v47
	s_cmp_lg_u32 s63, 0
	s_cbranch_scc1 .Leu_halo_skip_a0n0
	v_mul_u32_u24_e32 v58, 0xb000, v56
	v_lshl_add_u32 v58, v57, 5, v58
	s_mul_i32 s39, s12, 0x2c000
	s_lshl_b32 s40, s13, 9
	s_add_i32 s39, s39, s40
	s_lshl_b32 s40, s64, 2
	s_add_i32 s39, s39, s40
	s_add_u32 s20, s72, s39
	s_addc_u32 s21, s73, 0
	s_add_u32 s22, s20, 0x5800
	s_addc_u32 s23, s21, 0
	s_and_saveexec_b64 s[8:9], s[14:15]
	global_store_dwordx4 v58, v[192:195], s[20:21]
	global_store_dwordx4 v58, v[180:183], s[22:23]
	s_mov_b64 exec, s[8:9]
